# v24 + attention tile loop: one static s_setprio 1 for waves 4-7 (the staggered, later half), reset at unit exit
# baseline (speedup 1.0000x reference)
; __device__ __forceinline__ unsigned pk2(float lo, float hi) { return pg8::cvt_pk_bf16(lo, hi); }
; __device__ __forceinline__ void prompt_unit(LAS unsigned char* lds, const Ptrs& P, int qloc0, int qglob0, int kloc0, int kglob0, int h, int qb) {
;     ...
;     l += __shfl_xor(l, 32);
;     const float inv = 1.0f / l;
;     bf16_t* orow = P.ATT + (size_t)(qglob0 + 32 * wid + r32) * 1024 + h * 64;
; #pragma unroll
;     for (int db = 0; db < 2; ++db)
; #pragma unroll
;         for (int g = 0; g < 4; ++g) { u32x2 w; w.x = pk2(o[db][4 * g] * inv, o[db][4 * g + 1] * inv); w.y = pk2(o[db][4 * g + 2] * inv, o[db][4 * g + 3] * inv);
;             *(u32x2*)(orow + 32 * db + 8 * g + 4 * hi) = w; }
.Latt_no_catchup:
	s_setprio 0
	s_waitcnt lgkmcnt(0)
	v_lshlrev_b32_e32 v64, 3, v142
	s_mov_b64 s[66:67], 0
	v_add_f32_e32 v32, v135, v32
	v_div_scale_f32 v33, s[38:39], v32, v32, 1.0
	v_rcp_f32_e32 v34, v33
	s_nop 0
	v_fma_f32 v35, -v33, v34, 1.0
	v_fmac_f32_e32 v34, v35, v34
	v_div_scale_f32 v35, vcc, 1.0, v32, 1.0
	v_mul_f32_e32 v36, v35, v34
	v_fma_f32 v37, -v33, v36, v35
	v_fmac_f32_e32 v36, v37, v34
	v_fma_f32 v33, -v33, v36, v35
	v_div_fmas_f32 v33, v33, v34, v36
	v_div_fixup_f32 v34, v33, v32, 1.0
	v_add_u32_e32 v32, s27, v143
	v_ashrrev_i32_e32 v33, 31, v32
	v_lshlrev_b64 v[32:33], 11, v[32:33]
	v_lshl_add_u64 v[32:33], s[36:37], 0, v[32:33]
	v_lshl_add_u64 v[32:33], v[32:33], 0, v[64:65]
	v_lshl_add_u64 v[32:33], v[32:33], 0, v[64:65]
	v_mul_f32_e32 v0, v0, v34
	v_mul_f32_e32 v1, v1, v34
	v_mul_f32_e32 v2, v2, v34
	v_mul_f32_e32 v3, v3, v34
	v_mul_f32_e32 v4, v4, v34
	v_mul_f32_e32 v5, v5, v34
	v_mul_f32_e32 v6, v6, v34
	v_mul_f32_e32 v7, v7, v34
	v_mul_f32_e32 v8, v8, v34
	v_mul_f32_e32 v9, v9, v34
	v_mul_f32_e32 v10, v10, v34
	v_mul_f32_e32 v11, v11, v34
	v_mul_f32_e32 v12, v12, v34
	v_mul_f32_e32 v13, v13, v34
	v_mul_f32_e32 v14, v14, v34
	v_mul_f32_e32 v15, v15, v34
	v_mul_f32_e32 v16, v16, v34
	v_mul_f32_e32 v17, v17, v34
	v_mul_f32_e32 v18, v18, v34
	v_mul_f32_e32 v19, v19, v34
	v_mul_f32_e32 v20, v20, v34
	v_mul_f32_e32 v21, v21, v34
	v_mul_f32_e32 v22, v22, v34
	v_mul_f32_e32 v23, v23, v34
	v_mul_f32_e32 v24, v24, v34
	v_mul_f32_e32 v25, v25, v34
	v_mul_f32_e32 v26, v26, v34
	v_mul_f32_e32 v27, v27, v34
	v_mul_f32_e32 v28, v28, v34
	v_mul_f32_e32 v29, v29, v34
	v_mul_f32_e32 v30, v30, v34
	v_mul_f32_e32 v31, v31, v34
	v_cvt_pk_bf16_f32 v36, v16, v17
	v_cvt_pk_bf16_f32 v37, v18, v19
	v_cvt_pk_bf16_f32 v38, v20, v21
	v_cvt_pk_bf16_f32 v39, v22, v23
	s_nop 1
	v_permlane32_swap_b32_e32 v36, v38
	v_permlane32_swap_b32_e32 v37, v39
	global_store_dwordx4 v[32:33], v[36:39], off
	v_cvt_pk_bf16_f32 v40, v24, v25
	v_cvt_pk_bf16_f32 v41, v26, v27
	v_cvt_pk_bf16_f32 v42, v28, v29
	v_cvt_pk_bf16_f32 v43, v30, v31
	s_nop 1
	v_permlane32_swap_b32_e32 v40, v42
	v_permlane32_swap_b32_e32 v41, v43
	global_store_dwordx4 v[32:33], v[40:43], off offset:32
	v_cvt_pk_bf16_f32 v44, v0, v1
	v_cvt_pk_bf16_f32 v45, v2, v3
	v_cvt_pk_bf16_f32 v46, v4, v5
	v_cvt_pk_bf16_f32 v47, v6, v7
	s_nop 1
	v_permlane32_swap_b32_e32 v44, v46
	v_permlane32_swap_b32_e32 v45, v47
	global_store_dwordx4 v[32:33], v[44:47], off offset:64
	v_cvt_pk_bf16_f32 v48, v8, v9
	v_cvt_pk_bf16_f32 v49, v10, v11
	v_cvt_pk_bf16_f32 v50, v12, v13
	v_cvt_pk_bf16_f32 v51, v14, v15
	s_nop 1
	v_permlane32_swap_b32_e32 v48, v50
	v_permlane32_swap_b32_e32 v49, v51
	global_store_dwordx4 v[32:33], v[48:51], off offset:96
	s_and_b64 vcc, exec, s[64:65]
	s_cbranch_vccnz .LBB0_1139

; #define LAS __attribute__((address_space(3)))
; __device__ __forceinline__ void prompt_unit(LAS unsigned char* lds, const Ptrs& P, int qloc0, int qglob0, int kloc0, int kglob0, int h, int qb) {
;     ...
;     const bf16_t* kn_src = P.Kn + (size_t)(kloc0 + (tid >> 3)) * 1024 + h * 64 + (tid & 7) * 8;
;     const bf16_t* vt_src = P.Vt + (size_t)(h * 64 + (tid >> 3)) * VT_LD + kloc0 + (tid & 7) * 8;
;     const bf16_t* kr_src = P.KR + (size_t)(kglob0 + ((tid & 255) >> 2)) * 32 + (tid & 3) * 8;
;     const int k_w = (tid >> 3) * KP + (tid & 7) * 16, r_w = ((tid & 255) >> 2) * KP + 128 + (tid & 3) * 16;
;     const int v_w = KB + (tid >> 3) * VP + ((tid & 7) >> 1) * 32 + (tid & 1) * 8;
;     u32x4 kreg, vreg, rreg = (u32x4){0u, 0u, 0u, 0u};
;     kreg = *(const u32x4*)kn_src; vreg = *(const u32x4*)vt_src; if (tid < 256) rreg = *(const u32x4*)kr_src;
;     *(LAS u32x4*)(lds + k_w) = kreg; if (tid < 256) *(LAS u32x4*)(lds + r_w) = rreg;
;     *(LAS u32x2*)(lds + v_w) = (u32x2){vreg.x, vreg.y}; *(LAS u32x2*)(lds + v_w + 16) = (u32x2){vreg.z, vreg.w};
;     __syncthreads();
;     float m = -1e30f, l = 0.f; f32x16 o[2];
; #pragma unroll
;     for (int r = 0; r < 16; ++r) { o[0][r] = 0.f; o[1][r] = 0.f; }
;     for (int j = 0; j < NTL; ++j) {
;         const bool more = j + 1 < NTL;
;         if (more) { kreg = *(const u32x4*)(kn_src + (size_t)(j + 1) * 64 * 1024); vreg = *(const u32x4*)(vt_src + (j + 1) * 64); if (tid < 256) rreg = *(const u32x4*)(kr_src + (size_t)(j + 1) * 64 * 32); }
.LBB0_1149:
	s_or_b64 exec, exec, s[64:65]
	s_xor_b64 s[64:65], s[66:67], -1
	s_movk_i32 s67, 0x90
	v_mul_lo_u32 v4, v12, s67
	v_lshlrev_b32_e32 v6, 3, v16
	v_and_b32_e32 v5, 0x60, v8
	v_and_or_b32 v4, v6, 8, v4
	v_add_u32_e32 v148, v4, v5
	v_add_u32_e32 v4, 0, v148
	v_add_u32_e32 v4, 0x3000, v4
	s_lshl_b32 s66, s68, 2
	s_ashr_i32 s68, s69, 7
	s_waitcnt vmcnt(4)
	ds_write2_b64 v4, v[110:111], v[112:113] offset0:128 offset1:130
	v_lshlrev_b32_e32 v2, 4, v16
	s_add_i32 s69, s68, s66
	s_or_b32 s70, s66, 3
	v_mad_i64_i32 v[0:1], s[66:67], v12, s77, 0
	v_and_b32_e32 v2, 0x70, v2
	v_or_b32_e32 v0, v0, v2
	v_lshl_add_u64 v[136:137], s[40:41], 0, v[0:1]
	v_add_u32_e32 v0, s9, v13
	v_ashrrev_i32_e32 v1, 31, v0
	v_lshlrev_b64 v[0:1], 6, v[0:1]
	v_lshl_or_b32 v0, v9, 4, v0
	v_lshl_add_u64 v[138:139], s[96:97], 0, v[0:1]
	v_add_u32_e32 v0, s2, v12
	v_ashrrev_i32_e32 v1, 31, v0
	v_lshlrev_b64 v[0:1], 11, v[0:1]
	v_or_b32_e32 v0, v0, v2
	v_mul_u32_u24_e32 v147, 0xd0, v17
	v_mul_u32_u24_e32 v145, 0x90, v17
	v_add_u32_e32 v149, 0, v64
	v_lshl_add_u64 v[140:141], s[42:43], 0, v[0:1]
	s_mov_b64 s[66:67], 0x100
	v_lshl_add_u64 v[136:137], v[136:137], 0, s[66:67]
	s_mov_b64 s[66:67], 0x2000
	v_lshl_add_u64 v[138:139], v[138:139], 0, s[66:67]
	s_mov_b64 s[66:67], 0x40000
	s_mov_b32 s71, 0
	v_lshl_add_u64 v[140:141], v[140:141], 0, s[66:67]
	v_mov_b32_e32 v16, v65
	v_mov_b32_e32 v17, v65
	v_mov_b32_e32 v18, v65
	v_mov_b32_e32 v19, v65
	v_mov_b32_e32 v20, v65
	v_mov_b32_e32 v21, v65
	v_mov_b32_e32 v22, v65
	v_mov_b32_e32 v23, v65
	v_mov_b32_e32 v24, v65
	v_mov_b32_e32 v25, v65
	v_mov_b32_e32 v26, v65
	v_mov_b32_e32 v27, v65
	v_mov_b32_e32 v28, v65
	v_mov_b32_e32 v29, v65
	v_mov_b32_e32 v30, v65
	v_mov_b32_e32 v31, v65
	v_mov_b32_e32 v0, v65
	v_mov_b32_e32 v1, v65
	v_mov_b32_e32 v2, v65
	v_mov_b32_e32 v3, v65
	v_mov_b32_e32 v4, v65
	v_mov_b32_e32 v5, v65
	v_mov_b32_e32 v6, v65
	v_mov_b32_e32 v7, v65
	v_mov_b32_e32 v8, v65
	v_mov_b32_e32 v9, v65
	v_mov_b32_e32 v10, v65
	v_mov_b32_e32 v11, v65
	v_mov_b32_e32 v12, v65
	v_mov_b32_e32 v13, v65
	v_mov_b32_e32 v14, v65
	v_mov_b32_e32 v15, v65
	v_mov_b32_e32 v144, 0xf149f2ca
	v_mov_b32_e32 v135, 0
	s_waitcnt lgkmcnt(0)
	s_barrier
	s_mov_b32 s72, 0
	s_cmp_lt_u32 s68, 2
	s_cbranch_scc1 .LBB0_1151
	s_barrier
	s_setprio 1
